# P1 ada GEMM: MFMAs and A-fragment LDS reads of the padding row blocks (rows 144..255 of the 136-row problem, never stored) removed; W_in and W_rg conversions moved to the idle tail of the first up-pro
# speedup vs baseline: 1.0054x; 1.0054x over previous
; #define PG8_STAGE(bufoff, gbase, voff) do { _Pragma("unroll") for (int _i = 0; _i < 2; ++_i) \
;         __builtin_amdgcn_global_load_lds((const unsigned*)((const char*)(gbase) + (voff)[_i]), (LAS unsigned*)(lds + (bufoff) + ldsw + _i * 8192), 16, 0, 0); } while (0)
; #define PG8_LDA(dst, b, h) do { _Pragma("unroll") for (int m = 0; m < 4; ++m) _Pragma("unroll") for (int k = 0; k < 2; ++k) dst[m][k] = *(const LAS bf16x8*)(lds + PG8_SA(b, h) + aoff + m * 2048 + k * 1024); } while (0)
; #define PG8_LDB(dst, b, h) do { _Pragma("unroll") for (int n = 0; n < 2; ++n) _Pragma("unroll") for (int k = 0; k < 2; ++k) dst[n][k] = *(const LAS bf16x8*)(lds + PG8_SB(b, h) + boff + n * 2048 + k * 1024); } while (0)
; #define PG8_MMA(ai, bj, At, Bt) do { __builtin_amdgcn_s_setprio(1); _Pragma("unroll") for (int m = 0; m < 4; ++m) _Pragma("unroll") for (int n = 0; n < 2; ++n) _Pragma("unroll") for (int k = 0; k < 2; ++k) \
;         acc[ai][bj][m][n] = __builtin_amdgcn_mfma_f32_16x16x32_bf16(Bt[n][k], At[m][k], acc[ai][bj][m][n], 0, 0, 0); __builtin_amdgcn_s_setprio(0); } while (0)
; #define PG8_WAIT_V(n) asm volatile("s_waitcnt vmcnt(" #n ")" ::: "memory")
; #define PG8_WAIT_L(n) asm volatile("s_waitcnt lgkmcnt(" #n ")" ::: "memory")
; #define PG8_BAR __builtin_amdgcn_s_barrier()
; #define PG8_SCHED __builtin_amdgcn_sched_barrier(0)
; template <class Epi, class Sched>
; __device__ __forceinline__ void gemm_phase(LAS unsigned char* lds, const Gemm g, const Sched& S, const Epi& E, int wid) {
;     ...
;             PG8_LDB(B0, 0, 0); PG8_LDB(B1, 0, 1); PG8_SCHED; PG8_LDA(At, 0, 0); PG8_STAGE(PG8_SA(1, 1), a1 + hstep, voffA);
;             PG8_WAIT_V(8); PG8_WAIT_L(0); PG8_BAR; PG8_MMA(0, 0, At, B0); PG8_MMA(0, 1, At, B1); PG8_BAR; PG8_SCHED;
;             PG8_LDA(At, 0, 1); PG8_STAGE(PG8_SB(0, 0), b2, voffB); PG8_STAGE(PG8_SB(0, 1), b2 + hstep, voffB); PG8_STAGE(PG8_SA(0, 0), a2, voffA);
;             PG8_WAIT_V(8); PG8_WAIT_L(0); PG8_BAR; PG8_MMA(1, 0, At, B0); PG8_MMA(1, 1, At, B1); PG8_BAR; PG8_SCHED;
.LBB0_197:
	ds_read_b128 v[148:151], v145
	ds_read_b128 v[152:155], v145 offset:1024
	ds_read_b128 v[156:159], v145 offset:2048
	ds_read_b128 v[160:163], v145 offset:3072
	ds_read_b128 v[168:171], v146
	ds_read_b128 v[172:175], v146 offset:1024
	ds_read_b128 v[176:179], v146 offset:2048
	ds_read_b128 v[180:183], v146 offset:3072
	s_add_u32 s34, s30, 0xfffc0080
	s_addc_u32 s35, s31, -1
	s_cmp_eq_u32 s57, 12
	s_cselect_b32 s37, s21, s35
	s_cselect_b32 s36, s27, s34
	s_cselect_b32 s35, s19, s56
	s_cselect_b32 s34, s54, s55
	v_lshl_add_u64 v[140:141], s[30:31], 0, v[136:137]
	s_add_i32 m0, s29, 0xc000
	ds_read_b128 v[184:187], v147
	ds_read_b128 v[188:191], v147 offset:1024
	ds_read_b128 v[192:195], v147 offset:2048
	ds_read_b128 v[196:199], v147 offset:3072
	ds_read_b128 v[200:203], v147 offset:4096
	ds_read_b128 v[204:207], v147 offset:5120
	ds_read_b128 v[208:211], v147 offset:6144
	ds_read_b128 v[212:215], v147 offset:7168
	global_load_lds_dwordx4 v[140:141], off
	v_lshl_add_u64 v[140:141], s[30:31], 0, v[138:139]
	s_add_i32 m0, s29, 0xe000
	s_nop 0
	global_load_lds_dwordx4 v[140:141], off
	s_waitcnt vmcnt(8)
	s_waitcnt lgkmcnt(0)
	s_barrier
	s_setprio 1
	s_waitcnt lgkmcnt(0)
	v_mfma_f32_16x16x32_bf16 v[124:127], v[148:151], v[184:187], v[124:127]
	v_mfma_f32_16x16x32_bf16 v[120:123], v[156:159], v[184:187], v[120:123]
	v_mfma_f32_16x16x32_bf16 v[108:111], v[148:151], v[192:195], v[108:111]
	v_mfma_f32_16x16x32_bf16 v[104:107], v[156:159], v[192:195], v[104:107]
	v_mfma_f32_16x16x32_bf16 v[92:95], v[148:151], v[200:203], v[92:95]
	v_mfma_f32_16x16x32_bf16 v[88:91], v[156:159], v[200:203], v[88:91]
	v_mfma_f32_16x16x32_bf16 v[76:79], v[148:151], v[208:211], v[76:79]
	v_mfma_f32_16x16x32_bf16 v[72:75], v[156:159], v[208:211], v[72:75]
	v_mfma_f32_16x16x32_bf16 v[124:127], v[152:155], v[188:191], v[124:127]
	v_mfma_f32_16x16x32_bf16 v[120:123], v[160:163], v[188:191], v[120:123]
	v_mfma_f32_16x16x32_bf16 v[108:111], v[152:155], v[196:199], v[108:111]
	v_mfma_f32_16x16x32_bf16 v[104:107], v[160:163], v[196:199], v[104:107]
	v_mfma_f32_16x16x32_bf16 v[92:95], v[152:155], v[204:207], v[92:95]
	v_mfma_f32_16x16x32_bf16 v[88:91], v[160:163], v[204:207], v[88:91]
	v_mfma_f32_16x16x32_bf16 v[76:79], v[152:155], v[212:215], v[76:79]
	v_mfma_f32_16x16x32_bf16 v[72:75], v[160:163], v[212:215], v[72:75]
	s_setprio 0
	s_setprio 1
	v_mfma_f32_16x16x32_bf16 v[116:119], v[168:171], v[184:187], v[116:119]
	v_mfma_f32_16x16x32_bf16 v[112:115], v[176:179], v[184:187], v[112:115]
	v_mfma_f32_16x16x32_bf16 v[100:103], v[168:171], v[192:195], v[100:103]
	v_mfma_f32_16x16x32_bf16 v[96:99], v[176:179], v[192:195], v[96:99]
	v_mfma_f32_16x16x32_bf16 v[84:87], v[168:171], v[200:203], v[84:87]
	v_mfma_f32_16x16x32_bf16 v[80:83], v[176:179], v[200:203], v[80:83]
	v_mfma_f32_16x16x32_bf16 v[68:71], v[168:171], v[208:211], v[68:71]
	v_mfma_f32_16x16x32_bf16 v[64:67], v[176:179], v[208:211], v[64:67]
	v_mfma_f32_16x16x32_bf16 v[116:119], v[172:175], v[188:191], v[116:119]
	v_mfma_f32_16x16x32_bf16 v[112:115], v[180:183], v[188:191], v[112:115]
	v_mfma_f32_16x16x32_bf16 v[100:103], v[172:175], v[196:199], v[100:103]
	v_mfma_f32_16x16x32_bf16 v[96:99], v[180:183], v[196:199], v[96:99]
	v_mfma_f32_16x16x32_bf16 v[84:87], v[172:175], v[204:207], v[84:87]
	v_mfma_f32_16x16x32_bf16 v[80:83], v[180:183], v[204:207], v[80:83]
	v_mfma_f32_16x16x32_bf16 v[68:71], v[172:175], v[212:215], v[68:71]
	v_mfma_f32_16x16x32_bf16 v[64:67], v[180:183], v[212:215], v[64:67]
	s_setprio 0
	s_barrier
	s_add_i32 s58, s50, s75
	v_lshl_add_u64 v[140:141], s[34:35], 0, v[130:131]
	s_mov_b32 m0, s58
	ds_read_b128 v[184:187], v147 offset:16384
	ds_read_b128 v[188:191], v147 offset:17408
	global_load_lds_dwordx4 v[140:141], off
	s_add_i32 m0, s58, 0x2000
	s_add_u32 s58, s34, 0x40000
	v_lshl_add_u64 v[164:165], s[34:35], 0, v[134:135]
	s_addc_u32 s59, s35, 0
	s_add_i32 s60, s51, s75
	global_load_lds_dwordx4 v[164:165], off
	v_lshl_add_u64 v[216:217], s[58:59], 0, v[130:131]
	s_mov_b32 m0, s60
	v_lshl_add_u64 v[218:219], s[36:37], 0, v[132:133]
	global_load_lds_dwordx4 v[216:217], off
	v_lshl_add_u64 v[216:217], s[58:59], 0, v[134:135]
	s_add_i32 m0, s60, 0x2000
	s_nop 0
	global_load_lds_dwordx4 v[216:217], off
	v_lshl_add_u64 v[216:217], s[36:37], 0, v[128:129]
	s_mov_b32 m0, s29
	s_nop 0
	global_load_lds_dwordx4 v[216:217], off
	s_mov_b32 m0, s41
	s_nop 0
	global_load_lds_dwordx4 v[218:219], off
	s_waitcnt vmcnt(8)
	s_waitcnt lgkmcnt(0)
	s_barrier
	s_setprio 1
	s_waitcnt lgkmcnt(0)
	v_mfma_f32_16x16x32_bf16 v[60:63], v[148:151], v[184:187], v[60:63]
	v_mfma_f32_16x16x32_bf16 v[56:59], v[156:159], v[184:187], v[56:59]
	v_mfma_f32_16x16x32_bf16 v[60:63], v[152:155], v[188:191], v[60:63]
	v_mfma_f32_16x16x32_bf16 v[56:59], v[160:163], v[188:191], v[56:59]
	s_setprio 0
	s_setprio 1
	v_mfma_f32_16x16x32_bf16 v[52:55], v[168:171], v[184:187], v[52:55]
	v_mfma_f32_16x16x32_bf16 v[48:51], v[176:179], v[184:187], v[48:51]
	v_mfma_f32_16x16x32_bf16 v[52:55], v[172:175], v[188:191], v[52:55]
	v_mfma_f32_16x16x32_bf16 v[48:51], v[180:183], v[188:191], v[48:51]
	s_setprio 0
	s_barrier
; #define PG8_STAGE(bufoff, gbase, voff) do { _Pragma("unroll") for (int _i = 0; _i < 2; ++_i) \
;         __builtin_amdgcn_global_load_lds((const unsigned*)((const char*)(gbase) + (voff)[_i]), (LAS unsigned*)(lds + (bufoff) + ldsw + _i * 8192), 16, 0, 0); } while (0)
; #define PG8_LDA(dst, b, h) do { _Pragma("unroll") for (int m = 0; m < 4; ++m) _Pragma("unroll") for (int k = 0; k < 2; ++k) dst[m][k] = *(const LAS bf16x8*)(lds + PG8_SA(b, h) + aoff + m * 2048 + k * 1024); } while (0)
; #define PG8_LDB(dst, b, h) do { _Pragma("unroll") for (int n = 0; n < 2; ++n) _Pragma("unroll") for (int k = 0; k < 2; ++k) dst[n][k] = *(const LAS bf16x8*)(lds + PG8_SB(b, h) + boff + n * 2048 + k * 1024); } while (0)
; #define PG8_MMA(ai, bj, At, Bt) do { __builtin_amdgcn_s_setprio(1); _Pragma("unroll") for (int m = 0; m < 4; ++m) _Pragma("unroll") for (int n = 0; n < 2; ++n) _Pragma("unroll") for (int k = 0; k < 2; ++k) \
;         acc[ai][bj][m][n] = __builtin_amdgcn_mfma_f32_16x16x32_bf16(Bt[n][k], At[m][k], acc[ai][bj][m][n], 0, 0, 0); __builtin_amdgcn_s_setprio(0); } while (0)
; #define PG8_WAIT_V(n) asm volatile("s_waitcnt vmcnt(" #n ")" ::: "memory")
; #define PG8_WAIT_L(n) asm volatile("s_waitcnt lgkmcnt(" #n ")" ::: "memory")
; #define PG8_BAR __builtin_amdgcn_s_barrier()
; #define PG8_SCHED __builtin_amdgcn_sched_barrier(0)
; template <class Epi, class Sched>
; __device__ __forceinline__ void gemm_phase(LAS unsigned char* lds, const Gemm g, const Sched& S, const Epi& E, int wid) {
;     ...
;             PG8_LDB(B0, 1, 0); PG8_LDB(B1, 1, 1); PG8_SCHED; PG8_LDA(At, 1, 0); PG8_STAGE(PG8_SA(0, 1), a2 + hstep, voffA);
;             PG8_WAIT_V(8); PG8_WAIT_L(0); PG8_BAR; PG8_MMA(0, 0, At, B0); PG8_MMA(0, 1, At, B1); PG8_BAR; PG8_SCHED;
;             PG8_LDA(At, 1, 1); PG8_STAGE(PG8_SB(1, 0), b3, voffB); PG8_STAGE(PG8_SB(1, 1), b3 + hstep, voffB); PG8_STAGE(PG8_SA(1, 0), a3, voffA);
;             PG8_WAIT_V(8); PG8_WAIT_L(0); PG8_BAR; PG8_MMA(1, 0, At, B0); PG8_MMA(1, 1, At, B1); PG8_BAR; PG8_SCHED;
;         }
;         if (wr == 0) PG8_BAR;
	s_add_i32 s58, 0, 0x18000
	s_add_i32 s59, 0, 0x1c000
	v_add_u32_e32 v160, s58, v143
	v_add_u32_e32 v180, s59, v143
	ds_read_b128 v[148:151], v160
	ds_read_b128 v[152:155], v160 offset:1024
	ds_read_b128 v[156:159], v160 offset:2048
	ds_read_b128 v[160:163], v160 offset:3072
	ds_read_b128 v[168:171], v180
	ds_read_b128 v[172:175], v180 offset:1024
	ds_read_b128 v[176:179], v180 offset:2048
	ds_read_b128 v[180:183], v180 offset:3072
	s_add_u32 s36, s36, 0x40000
	s_addc_u32 s37, s37, 0
	s_mov_b32 m0, s42
	v_lshl_add_u64 v[220:221], s[36:37], 0, v[128:129]
	ds_read_b128 v[184:187], v147 offset:32768
	ds_read_b128 v[188:191], v147 offset:33792
	ds_read_b128 v[192:195], v147 offset:34816
	ds_read_b128 v[196:199], v147 offset:35840
	ds_read_b128 v[200:203], v147 offset:36864
	ds_read_b128 v[204:207], v147 offset:37888
	ds_read_b128 v[208:211], v147 offset:38912
	ds_read_b128 v[212:215], v147 offset:39936
	global_load_lds_dwordx4 v[220:221], off
	v_lshl_add_u64 v[220:221], s[36:37], 0, v[132:133]
	s_mov_b32 m0, s43
	s_nop 0
	global_load_lds_dwordx4 v[220:221], off
	s_waitcnt vmcnt(8)
	s_waitcnt lgkmcnt(0)
	s_barrier
	s_setprio 1
	s_waitcnt lgkmcnt(0)
	v_mfma_f32_16x16x32_bf16 v[124:127], v[148:151], v[184:187], v[124:127]
	v_mfma_f32_16x16x32_bf16 v[120:123], v[156:159], v[184:187], v[120:123]
	v_mfma_f32_16x16x32_bf16 v[108:111], v[148:151], v[192:195], v[108:111]
	v_mfma_f32_16x16x32_bf16 v[104:107], v[156:159], v[192:195], v[104:107]
	v_mfma_f32_16x16x32_bf16 v[92:95], v[148:151], v[200:203], v[92:95]
	v_mfma_f32_16x16x32_bf16 v[88:91], v[156:159], v[200:203], v[88:91]
	v_mfma_f32_16x16x32_bf16 v[76:79], v[148:151], v[208:211], v[76:79]
	v_mfma_f32_16x16x32_bf16 v[72:75], v[156:159], v[208:211], v[72:75]
	v_mfma_f32_16x16x32_bf16 v[124:127], v[152:155], v[188:191], v[124:127]
	v_mfma_f32_16x16x32_bf16 v[120:123], v[160:163], v[188:191], v[120:123]
	v_mfma_f32_16x16x32_bf16 v[108:111], v[152:155], v[196:199], v[108:111]
	v_mfma_f32_16x16x32_bf16 v[104:107], v[160:163], v[196:199], v[104:107]
	v_mfma_f32_16x16x32_bf16 v[92:95], v[152:155], v[204:207], v[92:95]
	v_mfma_f32_16x16x32_bf16 v[88:91], v[160:163], v[204:207], v[88:91]
	v_mfma_f32_16x16x32_bf16 v[76:79], v[152:155], v[212:215], v[76:79]
	v_mfma_f32_16x16x32_bf16 v[72:75], v[160:163], v[212:215], v[72:75]
	s_setprio 0
	s_setprio 1
	v_mfma_f32_16x16x32_bf16 v[116:119], v[168:171], v[184:187], v[116:119]
	v_mfma_f32_16x16x32_bf16 v[112:115], v[176:179], v[184:187], v[112:115]
	v_mfma_f32_16x16x32_bf16 v[100:103], v[168:171], v[192:195], v[100:103]
	v_mfma_f32_16x16x32_bf16 v[96:99], v[176:179], v[192:195], v[96:99]
	v_mfma_f32_16x16x32_bf16 v[84:87], v[168:171], v[200:203], v[84:87]
	v_mfma_f32_16x16x32_bf16 v[80:83], v[176:179], v[200:203], v[80:83]
	v_mfma_f32_16x16x32_bf16 v[68:71], v[168:171], v[208:211], v[68:71]
	v_mfma_f32_16x16x32_bf16 v[64:67], v[176:179], v[208:211], v[64:67]
	v_mfma_f32_16x16x32_bf16 v[116:119], v[172:175], v[188:191], v[116:119]
	v_mfma_f32_16x16x32_bf16 v[112:115], v[180:183], v[188:191], v[112:115]
	v_mfma_f32_16x16x32_bf16 v[100:103], v[172:175], v[196:199], v[100:103]
	v_mfma_f32_16x16x32_bf16 v[96:99], v[180:183], v[196:199], v[96:99]
	v_mfma_f32_16x16x32_bf16 v[84:87], v[172:175], v[204:207], v[84:87]
	v_mfma_f32_16x16x32_bf16 v[80:83], v[180:183], v[204:207], v[80:83]
	v_mfma_f32_16x16x32_bf16 v[68:71], v[172:175], v[212:215], v[68:71]
	v_mfma_f32_16x16x32_bf16 v[64:67], v[180:183], v[212:215], v[64:67]
	s_setprio 0
	s_barrier
	s_add_i32 s36, s58, s75
	v_lshl_add_u64 v[140:141], v[140:141], 0, s[10:11]
	s_mov_b32 m0, s36
	ds_read_b128 v[184:187], v147 offset:49152
	ds_read_b128 v[188:191], v147 offset:50176
	global_load_lds_dwordx4 v[140:141], off
	s_add_i32 m0, s36, 0x2000
	s_add_u32 s34, s34, 0x40080
	v_lshl_add_u64 v[140:141], v[164:165], 0, s[10:11]
	s_addc_u32 s35, s35, 0
	s_add_i32 s36, s59, s75
	global_load_lds_dwordx4 v[140:141], off
	v_lshl_add_u64 v[140:141], s[34:35], 0, v[130:131]
	s_mov_b32 m0, s36
	s_nop 0
	global_load_lds_dwordx4 v[140:141], off
	v_lshl_add_u64 v[140:141], s[34:35], 0, v[134:135]
	s_add_i32 m0, s36, 0x2000
	s_nop 0
	global_load_lds_dwordx4 v[140:141], off
	v_lshl_add_u64 v[140:141], v[216:217], 0, s[10:11]
	s_mov_b32 m0, s45
	s_nop 0
	global_load_lds_dwordx4 v[140:141], off
	v_lshl_add_u64 v[140:141], v[218:219], 0, s[10:11]
	s_mov_b32 m0, s46
	s_nop 0
	global_load_lds_dwordx4 v[140:141], off
	s_waitcnt vmcnt(8)
	s_waitcnt lgkmcnt(0)
	s_barrier
	s_setprio 1
	s_waitcnt lgkmcnt(0)
	v_mfma_f32_16x16x32_bf16 v[60:63], v[148:151], v[184:187], v[60:63]
	v_mfma_f32_16x16x32_bf16 v[56:59], v[156:159], v[184:187], v[56:59]
	v_mfma_f32_16x16x32_bf16 v[60:63], v[152:155], v[188:191], v[60:63]
	v_mfma_f32_16x16x32_bf16 v[56:59], v[160:163], v[188:191], v[56:59]
	s_setprio 0
	s_setprio 1
	v_mfma_f32_16x16x32_bf16 v[52:55], v[168:171], v[184:187], v[52:55]
	v_mfma_f32_16x16x32_bf16 v[48:51], v[176:179], v[184:187], v[48:51]
	v_mfma_f32_16x16x32_bf16 v[52:55], v[172:175], v[188:191], v[52:55]
	v_mfma_f32_16x16x32_bf16 v[48:51], v[180:183], v[188:191], v[48:51]
	s_setprio 0
	s_barrier
	s_add_i32 s57, s57, 2
	s_add_u32 s30, s30, 0x100
	s_addc_u32 s31, s31, 0
	s_add_u32 s55, s55, 0x100
	s_addc_u32 s56, s56, 0
	s_cmp_gt_u32 s57, 13
	s_cbranch_scc0 .LBB0_197
	s_and_b64 vcc, exec, s[14:15]
	s_cbranch_vccz .LBB0_200
	s_barrier

; template <int PART>
; __device__ __forceinline__ void prologue(const Params& P, LAS unsigned char* lds, int gw, int NGW, int wave, int lane) {
;     ...
;     for (int it = gw; it < NITEMS; it += NGW) {
;         int r = it;
;         if (PART == 0) { if (r >= I_ADA) break; r += I_FIRST; } else { if (r >= NITEMS - I_ADA) break; if (r >= I_FIRST) r += I_ADA; }
.LBB0_224:
	s_mov_b32 s12, 2
	s_cmp_eq_u32 s99, 0
	s_cbranch_scc0 .Lcv_tailmap
	s_cmpk_gt_i32 s26, 0x107f
	s_cbranch_scc1 .LBB0_319
	s_mov_b32 s22, s26
	s_cmpk_lt_i32 s26, 0xb00
	s_cbranch_scc1 .Lcv_go
	s_add_i32 s22, s26, 0xb00
	s_branch .Lcv_go
.Lcv_tailmap:
	s_cmp_eq_u32 s99, 1
	s_cbranch_scc0 .Lcv_tailmap3
	s_cmpk_gt_i32 s26, 0x167f
	s_cbranch_scc1 .LBB0_319
	s_add_i32 s22, s26, 0xb00
	s_cmpk_lt_i32 s26, 0xb00
	s_cbranch_scc1 .Lcv_go
	s_add_i32 s22, s26, 0x1080
	s_cmpk_lt_i32 s26, 0x1080
	s_cbranch_scc1 .Lcv_go
	s_add_i32 s22, s26, 0x2090
	s_branch .Lcv_go
.Lcv_tailmap3:
	s_cmpk_gt_i32 s26, 0x108f
	s_cbranch_scc1 .LBB0_319
	s_add_i32 s22, s26, 0x2100
	s_cmpk_lt_i32 s26, 0x1010
	s_cbranch_scc1 .Lcv_go
	s_add_i32 s22, s26, 0x3900

; __device__ __forceinline__ unsigned xb_add(unsigned* p, unsigned v) { return __hip_atomic_fetch_add(p, v, __ATOMIC_RELAXED, __HIP_MEMORY_SCOPE_AGENT); }
; __device__ __forceinline__ void xcd_barrier(const XcdBarrier& b, bool leader) {
;     asm volatile("s_waitcnt vmcnt(0)" ::: "memory");
;     __syncthreads();
;     if (leader) {
;         unsigned* bar = b.bar;
;         __builtin_amdgcn_s_waitcnt(0);
;         unsigned nloc = b.st[0], nx = b.st[1];
;         if (nloc == 0u) { xcd_barrier_complete(bar, b.x, nloc, nx); b.st[0] = nloc; b.st[1] = nx; }
;         const unsigned old = xb_add(&bar[XB_XSUB(b.x)], 1u);
;         const unsigned gen = old / nloc;
;         if (old + 1u == (gen + 1u) * nloc) {
.LBB0_345:
	s_cmp_eq_u32 s99, 1
	s_cbranch_scc1 .Lcv_ret
	s_cmp_eq_u32 s99, 2
	s_cbranch_scc1 .Lcv_ret3
	s_waitcnt vmcnt(0)
	s_waitcnt vmcnt(0) lgkmcnt(0)
	s_barrier
	s_and_saveexec_b64 s[4:5], s[88:89]
	s_cbranch_execz .LBB0_397
	s_add_i32 s6, 0, 0x23fc0
	v_mov_b32_e32 v0, s6
	s_waitcnt vmcnt(0) expcnt(0) lgkmcnt(0)
	ds_read_b32 v2, v0
	s_add_i32 s6, 0, 0x23fc4
	v_mov_b32_e32 v0, s6
	ds_read_b32 v0, v0
	s_waitcnt lgkmcnt(1)
	v_cmp_ne_u32_e32 vcc, 0, v2
	s_cbranch_vccnz .LBB0_361
	s_add_u32 s6, s76, 0x1000
	s_addc_u32 s7, s77, 0
	s_add_u32 s8, s76, 0x1100
	s_addc_u32 s9, s77, 0
	s_add_u32 s10, s76, 0x1200
	s_addc_u32 s11, s77, 0
	s_mul_i32 s20, s79, s74
	s_add_u32 s12, s76, 0x1300
	s_mul_i32 s20, s20, s78
	s_addc_u32 s13, s77, 0
	s_mov_b32 s21, 1
	v_mov_b32_e32 v16, 0
	s_branch .LBB0_349

; __global__ void __launch_bounds__(NTHR, 2) fwd_megakernel(Params P) {
;     ...
;     { pg8::Gemm g{H, (const bf16*)(ws + WS_WUP1), nullptr, nullptr, D}; pg8::StaticOrder S; S.init(MPAD, 2 * FF, G, wg);
;       EpiSwiglu E{ACT}; pg8::gemm_phase(lds, g, S, E, wave); }
.LBB0_498:
	s_cmpk_lt_u32 s2, 0x96
	s_cbranch_scc1 .Lcv_skip3
	s_mov_b32 s99, 2
	s_sub_i32 s72, s2, 0x96
	s_lshl_b32 s72, s72, 3
	s_add_i32 s72, s72, s3
	s_addk_i32 s72, 0x120
	s_movk_i32 s12, 0x470
	s_branch .Lcv_pre
.Lcv_ret3:
	s_mov_b32 s99, 0
	s_lshl_b32 s72, s2, 3
	s_add_i32 s72, s72, s3
